# dedicated converter workgroups in all three multi-round GEMM phases (14/12/14 WGs, tile stride 242/244/242), items rebalanced: gate2 split FFN1-gu/in-proj, w_in back in the prologue
# speedup vs baseline: 1.0100x; 1.0100x over previous
.LBB0_511:
	v_readlane_b32 s0, v234, 12
	v_writelane_b32 v233, s52, 12
	s_abs_i32 s52, s0
	v_cvt_f32_u32_e32 v0, s52
	s_sub_i32 s0, 0, s52
	v_readlane_b32 s1, v234, 13
	v_writelane_b32 v233, s50, 13
	v_rcp_iflag_f32_e32 v0, v0
	s_nop 0
	v_writelane_b32 v233, s51, 14
	v_mul_f32_e32 v0, 0x4f7ffffe, v0
	v_cvt_u32_f32_e32 v0, v0
	s_nop 0
	v_readfirstlane_b32 s53, v0
	s_mul_i32 s0, s0, s53
	s_mul_hi_u32 s0, s53, s0
	s_add_i32 s53, s53, s0
	s_mul_hi_u32 s0, s53, 0x5ac
	s_mul_i32 s0, s0, s52
	s_sub_i32 s0, 0x5ac, s0
	s_sub_i32 s1, s0, s52
	s_cmp_ge_u32 s0, s52
	s_cselect_b32 s0, s1, s0
	s_sub_i32 s1, s0, s52
	s_cmp_ge_u32 s0, s52
	s_movk_i32 s5, 0xf2
	s_cmp_eq_u32 s5, 0
	s_cselect_b64 s[0:1], -1, 0
	s_cmp_lt_i32 s4, s5
	s_cselect_b64 s[2:3], -1, 0
	s_or_b64 s[0:1], s[0:1], s[2:3]
	s_and_b64 vcc, exec, s[0:1]
	s_cbranch_vccnz .LBB0_931
	v_readlane_b32 s2, v234, 14
	v_readlane_b32 s3, v234, 12
	v_readfirstlane_b32 s0, v183
	s_sub_i32 s2, s2, s5
	s_sub_i32 s3, s3, s5
	s_lshl_b32 s2, s2, 3
	s_lshr_b32 s0, s0, 6
	s_add_i32 s4, s2, s0
	s_lshl_b32 s33, s3, 3
	s_cmp_ge_u32 s4, 0x10dc
	s_cbranch_scc1 .LBB0_931
	v_readlane_b32 s30, v234, 2
	v_readlane_b32 s31, v234, 3
	v_and_b32_e32 v176, 7, v183
	v_bfe_u32 v185, v183, 3, 3
	v_lshlrev_b32_e32 v177, 4, v185
	v_lshlrev_b32_e32 v186, 4, v176
	s_cmp_lt_u32 s4, 0x10dc
	s_cbranch_scc1 .Lcv1_p0_go
	s_mov_b32 s22, 0
	s_branch .Lcv1_p0_end

.Lcv1_p0_seg1:
	s_sub_u32 s34, s4, 0xb00
	s_mul_i32 s39, s34, 5958
	s_lshr_b32 s39, s39, 19
	s_mul_i32 s40, s39, 88
	s_sub_u32 s40, s34, s40
	v_readlane_b32 s0, v234, 4
	v_readlane_b32 s1, v234, 5
	s_mul_i32 s2, s39, 0x160000
	s_lshl_b32 s3, s40, 8
	s_add_u32 s2, s2, s3
	s_add_u32 s0, s0, s2
	s_addc_u32 s1, s1, 0
	s_mov_b32 s41, 0x5800
	s_mov_b32 s42, 0x2c000
	s_lshr_b32 s2, s40, 1
	s_lshl_b32 s2, s2, 8
	s_and_b32 s3, s40, 1
	s_lshl_b32 s3, s3, 6
	s_add_u32 s2, s2, s3
	s_mul_i32 s2, s2, 0x1000
	s_lshl_b32 s3, s39, 7
	s_add_u32 s2, s2, s3
	s_add_u32 s2, s2, 0x8700000
	s_add_u32 s16, s30, s2
	s_addc_u32 s17, s31, 0
	s_mov_b32 s20, 0x1000
	s_mov_b32 s21, 0x4000
	s_mov_b32 s23, -1
	v_readlane_b32 s8, v233, 6
	v_readlane_b32 s9, v233, 7
	s_lshl_b32 s3, s39, 8
	s_mov_b32 s22, 18
	s_nop 0
	s_add_u32 s8, s8, s3
	s_addc_u32 s9, s9, 0

.Lcv1_p0_end:
	s_cmp_lt_u32 s4, 0x10dc
	s_cbranch_scc1 .Lcv1_p1_go
	s_mov_b32 s28, 0
	s_branch .Lcv1_p1_end

.Lcv1_p1_seg1:
	s_sub_u32 s34, s4, 0xb00
	s_mul_i32 s39, s34, 5958
	s_lshr_b32 s39, s39, 19
	s_mul_i32 s40, s39, 88
	s_sub_u32 s40, s34, s40
	v_readlane_b32 s0, v234, 4
	v_readlane_b32 s1, v234, 5
	s_mul_i32 s2, s39, 0x160000
	s_lshl_b32 s3, s40, 8
	s_add_u32 s2, s2, s3
	s_add_u32 s0, s0, s2
	s_addc_u32 s1, s1, 0
	s_mov_b32 s41, 0x5800
	s_mov_b32 s42, 0x2c000
	s_lshr_b32 s2, s40, 1
	s_lshl_b32 s2, s2, 8
	s_and_b32 s3, s40, 1
	s_lshl_b32 s3, s3, 6
	s_add_u32 s2, s2, s3
	s_mul_i32 s2, s2, 0x1000
	s_lshl_b32 s3, s39, 7
	s_add_u32 s2, s2, s3
	s_add_u32 s2, s2, 0x8700000
	s_add_u32 s24, s30, s2
	s_addc_u32 s25, s31, 0
	s_mov_b32 s26, 0x1000
	s_mov_b32 s27, 0x4000
	s_mov_b32 s29, -1
	v_readlane_b32 s8, v233, 6
	v_readlane_b32 s9, v233, 7
	s_lshl_b32 s3, s39, 8
	s_mov_b32 s28, 18
	s_nop 0
	s_add_u32 s8, s8, s3
	s_addc_u32 s9, s9, 0

.Lcv1_pw_wd:
.Lcv1_loop:
	v_mad_u32_u24 v179, v185, s21, v186
	v_pk_mul_f32 v[0:1], v[0:1], v[128:129] op_sel_hi:[1,0]
	v_pk_mul_f32 v[2:3], v[2:3], v[128:129] op_sel_hi:[1,0]
	v_pk_mul_f32 v[4:5], v[4:5], v[128:129] op_sel_hi:[1,0]
	v_pk_mul_f32 v[6:7], v[6:7], v[128:129] op_sel_hi:[1,0]
	v_pk_mul_f32 v[8:9], v[8:9], v[128:129] op_sel:[0,1]
	v_pk_mul_f32 v[10:11], v[10:11], v[128:129] op_sel:[0,1]
	v_pk_mul_f32 v[12:13], v[12:13], v[128:129] op_sel:[0,1]
	v_pk_mul_f32 v[14:15], v[14:15], v[128:129] op_sel:[0,1]
	v_pk_mul_f32 v[16:17], v[16:17], v[130:131] op_sel_hi:[1,0]
	v_pk_mul_f32 v[18:19], v[18:19], v[130:131] op_sel_hi:[1,0]
	v_pk_mul_f32 v[20:21], v[20:21], v[130:131] op_sel_hi:[1,0]
	v_pk_mul_f32 v[22:23], v[22:23], v[130:131] op_sel_hi:[1,0]
	v_pk_mul_f32 v[24:25], v[24:25], v[130:131] op_sel:[0,1]
	v_pk_mul_f32 v[26:27], v[26:27], v[130:131] op_sel:[0,1]
	v_pk_mul_f32 v[28:29], v[28:29], v[130:131] op_sel:[0,1]
	v_pk_mul_f32 v[30:31], v[30:31], v[130:131] op_sel:[0,1]
	v_pk_mul_f32 v[32:33], v[32:33], v[132:133] op_sel_hi:[1,0]
	v_pk_mul_f32 v[34:35], v[34:35], v[132:133] op_sel_hi:[1,0]
	v_pk_mul_f32 v[36:37], v[36:37], v[132:133] op_sel_hi:[1,0]
	v_pk_mul_f32 v[38:39], v[38:39], v[132:133] op_sel_hi:[1,0]
	v_pk_mul_f32 v[40:41], v[40:41], v[132:133] op_sel:[0,1]
	v_pk_mul_f32 v[42:43], v[42:43], v[132:133] op_sel:[0,1]
	v_pk_mul_f32 v[44:45], v[44:45], v[132:133] op_sel:[0,1]
	v_pk_mul_f32 v[46:47], v[46:47], v[132:133] op_sel:[0,1]
	v_pk_mul_f32 v[48:49], v[48:49], v[134:135] op_sel_hi:[1,0]
	v_pk_mul_f32 v[50:51], v[50:51], v[134:135] op_sel_hi:[1,0]
	v_pk_mul_f32 v[52:53], v[52:53], v[134:135] op_sel_hi:[1,0]
	v_pk_mul_f32 v[54:55], v[54:55], v[134:135] op_sel_hi:[1,0]
	v_pk_mul_f32 v[56:57], v[56:57], v[134:135] op_sel:[0,1]
	v_pk_mul_f32 v[58:59], v[58:59], v[134:135] op_sel:[0,1]
	v_pk_mul_f32 v[60:61], v[60:61], v[134:135] op_sel:[0,1]
	v_pk_mul_f32 v[62:63], v[62:63], v[134:135] op_sel:[0,1]
	v_cvt_pk_bf16_f32 v144, v0, v8
	v_cvt_pk_bf16_f32 v145, v16, v24
	v_cvt_pk_bf16_f32 v146, v32, v40
	v_cvt_pk_bf16_f32 v147, v48, v56
	global_store_dwordx4 v179, v[144:147], s[16:17]
	v_cvt_pk_bf16_f32 v148, v1, v9
	v_cvt_pk_bf16_f32 v149, v17, v25
	v_cvt_pk_bf16_f32 v150, v33, v41
	v_cvt_pk_bf16_f32 v151, v49, v57
	s_add_u32 s16, s16, s20
	s_addc_u32 s17, s17, 0
	global_store_dwordx4 v179, v[148:151], s[16:17]
	v_cvt_pk_bf16_f32 v152, v2, v10
	v_cvt_pk_bf16_f32 v153, v18, v26
	v_cvt_pk_bf16_f32 v154, v34, v42
	v_cvt_pk_bf16_f32 v155, v50, v58
	s_add_u32 s16, s16, s20
	s_addc_u32 s17, s17, 0
	global_store_dwordx4 v179, v[152:155], s[16:17]
	v_cvt_pk_bf16_f32 v156, v3, v11
	v_cvt_pk_bf16_f32 v157, v19, v27
	v_cvt_pk_bf16_f32 v158, v35, v43
	v_cvt_pk_bf16_f32 v159, v51, v59
	s_add_u32 s16, s16, s20
	s_addc_u32 s17, s17, 0
	global_store_dwordx4 v179, v[156:159], s[16:17]
	v_cvt_pk_bf16_f32 v160, v4, v12
	v_cvt_pk_bf16_f32 v161, v20, v28
	v_cvt_pk_bf16_f32 v162, v36, v44
	v_cvt_pk_bf16_f32 v163, v52, v60
	s_mul_i32 s2, s20, 29
	s_add_u32 s16, s16, s2
	s_addc_u32 s17, s17, 0
	global_store_dwordx4 v179, v[160:163], s[16:17]
	v_cvt_pk_bf16_f32 v164, v5, v13
	v_cvt_pk_bf16_f32 v165, v21, v29
	v_cvt_pk_bf16_f32 v166, v37, v45
	v_cvt_pk_bf16_f32 v167, v53, v61
	s_add_u32 s16, s16, s20
	s_addc_u32 s17, s17, 0
	global_store_dwordx4 v179, v[164:167], s[16:17]
	v_cvt_pk_bf16_f32 v168, v6, v14
	v_cvt_pk_bf16_f32 v169, v22, v30
	v_cvt_pk_bf16_f32 v170, v38, v46
	v_cvt_pk_bf16_f32 v171, v54, v62
	s_add_u32 s16, s16, s20
	s_addc_u32 s17, s17, 0
	global_store_dwordx4 v179, v[168:171], s[16:17]
	v_cvt_pk_bf16_f32 v172, v7, v15
	v_cvt_pk_bf16_f32 v173, v23, v31
	v_cvt_pk_bf16_f32 v174, v39, v47
	v_cvt_pk_bf16_f32 v175, v55, v63
	s_add_u32 s16, s16, s20
	s_addc_u32 s17, s17, 0
	global_store_dwordx4 v179, v[172:175], s[16:17]
	s_cmp_lt_u32 s4, 0x10dc
	s_cbranch_scc1 .Lcv1_la_go
	s_mov_b32 s22, 0
	s_branch .Lcv1_la_end

.Lcv1_wb_wd:
	v_mad_u32_u24 v179, v185, s27, v186
	v_pk_mul_f32 v[64:65], v[64:65], v[136:137] op_sel_hi:[1,0]
	v_pk_mul_f32 v[66:67], v[66:67], v[136:137] op_sel_hi:[1,0]
	v_pk_mul_f32 v[68:69], v[68:69], v[136:137] op_sel_hi:[1,0]
	v_pk_mul_f32 v[70:71], v[70:71], v[136:137] op_sel_hi:[1,0]
	v_pk_mul_f32 v[72:73], v[72:73], v[136:137] op_sel:[0,1]
	v_pk_mul_f32 v[74:75], v[74:75], v[136:137] op_sel:[0,1]
	v_pk_mul_f32 v[76:77], v[76:77], v[136:137] op_sel:[0,1]
	v_pk_mul_f32 v[78:79], v[78:79], v[136:137] op_sel:[0,1]
	v_pk_mul_f32 v[80:81], v[80:81], v[138:139] op_sel_hi:[1,0]
	v_pk_mul_f32 v[82:83], v[82:83], v[138:139] op_sel_hi:[1,0]
	v_pk_mul_f32 v[84:85], v[84:85], v[138:139] op_sel_hi:[1,0]
	v_pk_mul_f32 v[86:87], v[86:87], v[138:139] op_sel_hi:[1,0]
	v_pk_mul_f32 v[88:89], v[88:89], v[138:139] op_sel:[0,1]
	v_pk_mul_f32 v[90:91], v[90:91], v[138:139] op_sel:[0,1]
	v_pk_mul_f32 v[92:93], v[92:93], v[138:139] op_sel:[0,1]
	v_pk_mul_f32 v[94:95], v[94:95], v[138:139] op_sel:[0,1]
	v_pk_mul_f32 v[96:97], v[96:97], v[140:141] op_sel_hi:[1,0]
	v_pk_mul_f32 v[98:99], v[98:99], v[140:141] op_sel_hi:[1,0]
	v_pk_mul_f32 v[100:101], v[100:101], v[140:141] op_sel_hi:[1,0]
	v_pk_mul_f32 v[102:103], v[102:103], v[140:141] op_sel_hi:[1,0]
	v_pk_mul_f32 v[104:105], v[104:105], v[140:141] op_sel:[0,1]
	v_pk_mul_f32 v[106:107], v[106:107], v[140:141] op_sel:[0,1]
	v_pk_mul_f32 v[108:109], v[108:109], v[140:141] op_sel:[0,1]
	v_pk_mul_f32 v[110:111], v[110:111], v[140:141] op_sel:[0,1]
	v_pk_mul_f32 v[112:113], v[112:113], v[142:143] op_sel_hi:[1,0]
	v_pk_mul_f32 v[114:115], v[114:115], v[142:143] op_sel_hi:[1,0]
	v_pk_mul_f32 v[116:117], v[116:117], v[142:143] op_sel_hi:[1,0]
	v_pk_mul_f32 v[118:119], v[118:119], v[142:143] op_sel_hi:[1,0]
	v_pk_mul_f32 v[120:121], v[120:121], v[142:143] op_sel:[0,1]
	v_pk_mul_f32 v[122:123], v[122:123], v[142:143] op_sel:[0,1]
	v_pk_mul_f32 v[124:125], v[124:125], v[142:143] op_sel:[0,1]
	v_pk_mul_f32 v[126:127], v[126:127], v[142:143] op_sel:[0,1]
	v_cvt_pk_bf16_f32 v144, v64, v72
	v_cvt_pk_bf16_f32 v145, v80, v88
	v_cvt_pk_bf16_f32 v146, v96, v104
	v_cvt_pk_bf16_f32 v147, v112, v120
	global_store_dwordx4 v179, v[144:147], s[24:25]
	v_cvt_pk_bf16_f32 v148, v65, v73
	v_cvt_pk_bf16_f32 v149, v81, v89
	v_cvt_pk_bf16_f32 v150, v97, v105
	v_cvt_pk_bf16_f32 v151, v113, v121
	s_add_u32 s24, s24, s26
	s_addc_u32 s25, s25, 0
	global_store_dwordx4 v179, v[148:151], s[24:25]
	v_cvt_pk_bf16_f32 v152, v66, v74
	v_cvt_pk_bf16_f32 v153, v82, v90
	v_cvt_pk_bf16_f32 v154, v98, v106
	v_cvt_pk_bf16_f32 v155, v114, v122
	s_add_u32 s24, s24, s26
	s_addc_u32 s25, s25, 0
	global_store_dwordx4 v179, v[152:155], s[24:25]
	v_cvt_pk_bf16_f32 v156, v67, v75
	v_cvt_pk_bf16_f32 v157, v83, v91
	v_cvt_pk_bf16_f32 v158, v99, v107
	v_cvt_pk_bf16_f32 v159, v115, v123
	s_add_u32 s24, s24, s26
	s_addc_u32 s25, s25, 0
	global_store_dwordx4 v179, v[156:159], s[24:25]
	v_cvt_pk_bf16_f32 v160, v68, v76
	v_cvt_pk_bf16_f32 v161, v84, v92
	v_cvt_pk_bf16_f32 v162, v100, v108
	v_cvt_pk_bf16_f32 v163, v116, v124
	s_mul_i32 s2, s26, 29
	s_add_u32 s24, s24, s2
	s_addc_u32 s25, s25, 0
	global_store_dwordx4 v179, v[160:163], s[24:25]
	v_cvt_pk_bf16_f32 v164, v69, v77
	v_cvt_pk_bf16_f32 v165, v85, v93
	v_cvt_pk_bf16_f32 v166, v101, v109
	v_cvt_pk_bf16_f32 v167, v117, v125
	s_add_u32 s24, s24, s26
	s_addc_u32 s25, s25, 0
	global_store_dwordx4 v179, v[164:167], s[24:25]
	v_cvt_pk_bf16_f32 v168, v70, v78
	v_cvt_pk_bf16_f32 v169, v86, v94
	v_cvt_pk_bf16_f32 v170, v102, v110
	v_cvt_pk_bf16_f32 v171, v118, v126
	s_add_u32 s24, s24, s26
	s_addc_u32 s25, s25, 0
	global_store_dwordx4 v179, v[168:171], s[24:25]
	v_cvt_pk_bf16_f32 v172, v71, v79
	v_cvt_pk_bf16_f32 v173, v87, v95
	v_cvt_pk_bf16_f32 v174, v103, v111
	v_cvt_pk_bf16_f32 v175, v119, v127
	s_add_u32 s24, s24, s26
	s_addc_u32 s25, s25, 0
	global_store_dwordx4 v179, v[172:175], s[24:25]
	s_cmp_lt_u32 s4, 0x10dc
	s_cbranch_scc1 .Lcv1_lb_go
	s_mov_b32 s28, 0
	s_branch .Lcv1_lb_end

.LBB0_1095:
	s_or_b64 exec, exec, s[0:1]
	v_readlane_b32 s0, v234, 14
	v_mov_b32_e32 v8, v183
	s_cmpk_lt_i32 s0, 0xf4
	s_waitcnt lgkmcnt(0)
	s_barrier
	s_cselect_b64 s[2:3], -1, 0
	s_cmpk_gt_i32 s0, 0xf3
	v_readfirstlane_b32 s4, v8
	s_cbranch_scc1 .LBB0_1101
	v_readlane_b32 s1, v234, 14
	s_ashr_i32 s0, s1, 31
	s_lshr_b32 s0, s0, 29
	s_add_i32 s5, s1, s0
	s_and_b32 s0, s5, -8
	s_sub_i32 s6, s1, s0
	s_cmp_gt_i32 s6, 2
	s_cbranch_scc0 .LBB0_1098
	s_mul_i32 s0, s6, 0xf3
	s_add_i32 s7, s0, 3
	s_cbranch_execz .LBB0_1099
	s_branch .LBB0_1100

.LBB0_1104:
	v_lshrrev_b32_e32 v16, 1, v8
	v_and_b32_e32 v15, 15, v8
	v_and_b32_e32 v16, 24, v16
	s_and_b32 s1, s5, 3
	v_lshl_or_b32 v153, s20, 6, v15
	v_lshlrev_b32_e32 v17, 1, v16
	s_lshl_b32 s5, s20, 13
	v_lshlrev_b32_e32 v8, 2, v8
	s_mov_b64 s[20:21], 0x80
	v_lshl_or_b32 v15, v15, 6, v17
	v_and_b32_e32 v8, 32, v8
	s_add_i32 m0, s40, 0x18000
	v_lshl_add_u64 v[6:7], v[6:7], 0, s[20:21]
	v_bitop3_b32 v17, v15, s5, v8 bitop3:0xde
	s_lshl_b32 s5, s1, 12
	s_waitcnt vmcnt(2)
	s_barrier
	global_load_lds_dwordx4 v[6:7], off
	v_lshl_add_u64 v[4:5], v[4:5], 0, s[20:21]
	s_add_i32 m0, s40, 0x1a000
	s_add_i32 s45, s40, 0x8000
	s_add_i32 s46, s40, 0xa000
	global_load_lds_dwordx4 v[4:5], off
	v_lshl_add_u64 v[0:1], v[0:1], 0, s[20:21]
	s_mov_b32 m0, s45
	s_add_u32 s22, s36, 0x80080
	global_load_lds_dwordx4 v[0:1], off
	v_lshl_add_u64 v[0:1], v[2:3], 0, s[20:21]
	s_mov_b32 m0, s46
	s_addc_u32 s23, s37, 0
	global_load_lds_dwordx4 v[0:1], off
	s_add_i32 m0, s40, 0x1c000
	v_lshl_add_u64 v[0:1], s[22:23], 0, v[130:131]
	global_load_lds_dwordx4 v[0:1], off
	v_lshl_add_u64 v[0:1], s[22:23], 0, v[134:135]
	s_add_i32 m0, s40, 0x1e000
	s_cmpk_lt_u32 s4, 0x100
	global_load_lds_dwordx4 v[0:1], off
	v_bitop3_b32 v154, v15, s5, v8 bitop3:0xde
	s_cselect_b64 s[22:23], -1, 0
	s_cmp_lt_u32 s1, 2
	v_readlane_b32 s4, v234, 12
	s_cselect_b64 s[24:25], -1, 0
	v_readlane_b32 s5, v234, 13
	s_ashr_i32 s47, s4, 31
	s_movk_i32 s48, 0xf4
	v_readlane_b32 s4, v234, 14
	s_ashr_i32 s49, s4, 31
	s_lshl_b32 s4, s1, 7
	v_readlane_b32 s5, v233, 19
	s_add_u32 s4, s5, s4
	v_readlane_b32 s5, v233, 20
	s_addc_u32 s5, s5, 0
	v_lshlrev_b32_e32 v0, 2, v16
	v_mov_b32_e32 v1, v131
	v_lshl_add_u64 v[136:137], s[4:5], 0, v[0:1]
	v_lshlrev_b32_e32 v0, 15, v9
	v_and_b32_e32 v0, 0xffff0000, v0
	v_lshl_add_u32 v0, v10, 12, v0
	v_and_b32_e32 v1, 1, v9
	v_lshl_or_b32 v0, v1, 6, v0
	v_lshl_add_u32 v138, v11, 1, v0
	v_lshlrev_b32_e32 v0, 15, v12
	v_and_b32_e32 v0, 0xffff0000, v0
	s_waitcnt vmcnt(6)
	v_lshl_add_u32 v0, v13, 12, v0
	v_and_b32_e32 v1, 1, v12
	v_lshl_or_b32 v0, v1, 6, v0
	s_add_i32 s50, 0, 0x10000
	s_add_i32 s51, 0, 0x14000
	v_lshl_or_b32 v155, s1, 5, v16
	v_mov_b32_e32 v139, v131
	v_lshl_add_u32 v140, v14, 1, v0
	v_mov_b32_e32 v141, v131
	v_mov_b64_e32 v[142:143], 0x79b
	v_mov_b64_e32 v[144:145], 0x79a
	v_add_u32_e32 v156, s50, v154
	v_add_u32_e32 v157, s51, v154
	v_add_u32_e32 v158, 0, v17
	v_mov_b32_e32 v159, 0x358637bd
	s_mov_b32 s54, 0x800000
	s_movk_i32 s55, 0x7400
	s_barrier
	s_branch .LBB0_1107

.LBB0_1169:
	s_mul_hi_u32 s0, s53, 0x79b
	s_mul_i32 s0, s0, s52
	s_sub_i32 s0, 0x79b, s0
	s_sub_i32 s1, s0, s52
	s_cmp_ge_u32 s0, s52
	s_cselect_b32 s0, s1, s0
	s_sub_i32 s1, s0, s52
	s_cmp_ge_u32 s0, s52
	s_movk_i32 s7, 0xf4
	s_cmp_lg_u32 s7, 0
	v_readlane_b32 s2, v234, 14
	s_cselect_b64 s[0:1], -1, 0
	s_cmp_ge_i32 s2, s7
	s_cselect_b64 s[2:3], -1, 0
	s_and_b64 s[0:1], s[0:1], s[2:3]
	s_and_b64 vcc, exec, s[0:1]
	s_cbranch_vccz .LBB0_1605
	v_readlane_b32 s2, v234, 14
	v_readlane_b32 s3, v234, 12
	v_readfirstlane_b32 s0, v183
	s_sub_i32 s2, s2, s7
	s_sub_i32 s3, s3, s7
	s_lshl_b32 s2, s2, 3
	s_lshr_b32 s0, s0, 6
	s_add_i32 s4, s2, s0
	s_lshl_b32 s33, s3, 3
	s_cmp_ge_u32 s4, 0x1424
	s_cbranch_scc1 .LBB0_1605
	v_readlane_b32 s30, v234, 2
	v_readlane_b32 s31, v234, 3
	v_and_b32_e32 v176, 7, v183
	v_bfe_u32 v185, v183, 3, 3
	v_lshlrev_b32_e32 v177, 4, v185
	v_lshlrev_b32_e32 v186, 4, v176
	s_cmp_lt_u32 s4, 0x1424
	s_cbranch_scc1 .Lcv2_p0_go
	s_mov_b32 s22, 0
	s_branch .Lcv2_p0_end

.Lcv2_p0_seg1:
	s_cmp_lt_u32 s4, 0x924
	s_cbranch_scc0 .Lcv2_p0_seg2
	s_add_u32 s34, s4, 0x1dc
	s_mul_i32 s39, s34, 5958
	s_lshr_b32 s39, s39, 19
	s_mul_i32 s40, s39, 88
	s_sub_u32 s40, s34, s40
	v_readlane_b32 s0, v234, 4
	v_readlane_b32 s1, v234, 5
	s_mul_i32 s2, s39, 0x160000
	s_lshl_b32 s3, s40, 8
	s_add_u32 s2, s2, s3
	s_add_u32 s0, s0, s2
	s_addc_u32 s1, s1, 0
	s_mov_b32 s41, 0x5800
	s_mov_b32 s42, 0x2c000
	s_lshr_b32 s2, s40, 1
	s_lshl_b32 s2, s2, 8
	s_and_b32 s3, s40, 1
	s_lshl_b32 s3, s3, 6
	s_add_u32 s2, s2, s3
	s_mul_i32 s2, s2, 0x1000
	s_lshl_b32 s3, s39, 7
	s_add_u32 s2, s2, s3
	s_add_u32 s2, s2, 0x8700000
	s_add_u32 s16, s30, s2
	s_addc_u32 s17, s31, 0
	s_mov_b32 s20, 0x1000
	s_mov_b32 s21, 0x4000
	s_mov_b32 s23, -1
	v_readlane_b32 s8, v233, 6
	v_readlane_b32 s9, v233, 7
	s_lshl_b32 s3, s39, 8
	s_mov_b32 s22, 18
	s_nop 0
	s_add_u32 s8, s8, s3
	s_addc_u32 s9, s9, 0
	s_branch .Lcv2_p0_ld
.Lcv2_p0_seg2:
	s_sub_u32 s34, s4, 0x924
	s_mul_i32 s39, s34, 5958
	s_lshr_b32 s39, s39, 19
	s_mul_i32 s40, s39, 88
	s_sub_u32 s40, s34, s40
	v_readlane_b32 s0, v234, 6
	v_readlane_b32 s1, v234, 7
	s_mul_i32 s2, s39, 0x160000
	s_lshl_b32 s3, s40, 8
	s_add_u32 s2, s2, s3
	s_add_u32 s0, s0, s2
	s_addc_u32 s1, s1, 0
	s_mov_b32 s41, 0x5800
	s_mov_b32 s42, 0x2c000
	s_lshr_b32 s2, s40, 1
	s_lshl_b32 s2, s2, 8
	s_and_b32 s3, s40, 1
	s_lshl_b32 s3, s3, 6
	s_add_u32 s2, s2, s3
	s_add_u32 s2, s2, 0x80
	s_mul_i32 s2, s2, 0x1000
	s_lshl_b32 s3, s39, 7
	s_add_u32 s2, s2, s3
	s_add_u32 s2, s2, 0x8700000
	s_add_u32 s16, s30, s2
	s_addc_u32 s17, s31, 0
	s_mov_b32 s20, 0x1000
	s_mov_b32 s21, 0x4000
	s_mov_b32 s23, -1
	v_readlane_b32 s8, v233, 6
	v_readlane_b32 s9, v233, 7
	s_lshl_b32 s3, s39, 8
	s_mov_b32 s22, 18
	s_nop 0
	s_add_u32 s8, s8, s3
	s_addc_u32 s9, s9, 0

.Lcv2_p0_end:
	s_cmp_lt_u32 s4, 0x1424
	s_cbranch_scc1 .Lcv2_p1_go
	s_mov_b32 s28, 0
	s_branch .Lcv2_p1_end

.Lcv2_p1_seg1:
	s_cmp_lt_u32 s4, 0x924
	s_cbranch_scc0 .Lcv2_p1_seg2
	s_add_u32 s34, s4, 0x1dc
	s_mul_i32 s39, s34, 5958
	s_lshr_b32 s39, s39, 19
	s_mul_i32 s40, s39, 88
	s_sub_u32 s40, s34, s40
	v_readlane_b32 s0, v234, 4
	v_readlane_b32 s1, v234, 5
	s_mul_i32 s2, s39, 0x160000
	s_lshl_b32 s3, s40, 8
	s_add_u32 s2, s2, s3
	s_add_u32 s0, s0, s2
	s_addc_u32 s1, s1, 0
	s_mov_b32 s41, 0x5800
	s_mov_b32 s42, 0x2c000
	s_lshr_b32 s2, s40, 1
	s_lshl_b32 s2, s2, 8
	s_and_b32 s3, s40, 1
	s_lshl_b32 s3, s3, 6
	s_add_u32 s2, s2, s3
	s_mul_i32 s2, s2, 0x1000
	s_lshl_b32 s3, s39, 7
	s_add_u32 s2, s2, s3
	s_add_u32 s2, s2, 0x8700000
	s_add_u32 s24, s30, s2
	s_addc_u32 s25, s31, 0
	s_mov_b32 s26, 0x1000
	s_mov_b32 s27, 0x4000
	s_mov_b32 s29, -1
	v_readlane_b32 s8, v233, 6
	v_readlane_b32 s9, v233, 7
	s_lshl_b32 s3, s39, 8
	s_mov_b32 s28, 18
	s_nop 0
	s_add_u32 s8, s8, s3
	s_addc_u32 s9, s9, 0
	s_branch .Lcv2_p1_ld
.Lcv2_p1_seg2:
	s_sub_u32 s34, s4, 0x924
	s_mul_i32 s39, s34, 5958
	s_lshr_b32 s39, s39, 19
	s_mul_i32 s40, s39, 88
	s_sub_u32 s40, s34, s40
	v_readlane_b32 s0, v234, 6
	v_readlane_b32 s1, v234, 7
	s_mul_i32 s2, s39, 0x160000
	s_lshl_b32 s3, s40, 8
	s_add_u32 s2, s2, s3
	s_add_u32 s0, s0, s2
	s_addc_u32 s1, s1, 0
	s_mov_b32 s41, 0x5800
	s_mov_b32 s42, 0x2c000
	s_lshr_b32 s2, s40, 1
	s_lshl_b32 s2, s2, 8
	s_and_b32 s3, s40, 1
	s_lshl_b32 s3, s3, 6
	s_add_u32 s2, s2, s3
	s_add_u32 s2, s2, 0x80
	s_mul_i32 s2, s2, 0x1000
	s_lshl_b32 s3, s39, 7
	s_add_u32 s2, s2, s3
	s_add_u32 s2, s2, 0x8700000
	s_add_u32 s24, s30, s2
	s_addc_u32 s25, s31, 0
	s_mov_b32 s26, 0x1000
	s_mov_b32 s27, 0x4000
	s_mov_b32 s29, -1
	v_readlane_b32 s8, v233, 6
	v_readlane_b32 s9, v233, 7
	s_lshl_b32 s3, s39, 8
	s_mov_b32 s28, 18
	s_nop 0
	s_add_u32 s8, s8, s3
	s_addc_u32 s9, s9, 0

.Lcv2_pw_wd:
.Lcv2_loop:
	v_mad_u32_u24 v179, v185, s21, v186
	v_pk_mul_f32 v[0:1], v[0:1], v[128:129] op_sel_hi:[1,0]
	v_pk_mul_f32 v[2:3], v[2:3], v[128:129] op_sel_hi:[1,0]
	v_pk_mul_f32 v[4:5], v[4:5], v[128:129] op_sel_hi:[1,0]
	v_pk_mul_f32 v[6:7], v[6:7], v[128:129] op_sel_hi:[1,0]
	v_pk_mul_f32 v[8:9], v[8:9], v[128:129] op_sel:[0,1]
	v_pk_mul_f32 v[10:11], v[10:11], v[128:129] op_sel:[0,1]
	v_pk_mul_f32 v[12:13], v[12:13], v[128:129] op_sel:[0,1]
	v_pk_mul_f32 v[14:15], v[14:15], v[128:129] op_sel:[0,1]
	v_pk_mul_f32 v[16:17], v[16:17], v[130:131] op_sel_hi:[1,0]
	v_pk_mul_f32 v[18:19], v[18:19], v[130:131] op_sel_hi:[1,0]
	v_pk_mul_f32 v[20:21], v[20:21], v[130:131] op_sel_hi:[1,0]
	v_pk_mul_f32 v[22:23], v[22:23], v[130:131] op_sel_hi:[1,0]
	v_pk_mul_f32 v[24:25], v[24:25], v[130:131] op_sel:[0,1]
	v_pk_mul_f32 v[26:27], v[26:27], v[130:131] op_sel:[0,1]
	v_pk_mul_f32 v[28:29], v[28:29], v[130:131] op_sel:[0,1]
	v_pk_mul_f32 v[30:31], v[30:31], v[130:131] op_sel:[0,1]
	v_pk_mul_f32 v[32:33], v[32:33], v[132:133] op_sel_hi:[1,0]
	v_pk_mul_f32 v[34:35], v[34:35], v[132:133] op_sel_hi:[1,0]
	v_pk_mul_f32 v[36:37], v[36:37], v[132:133] op_sel_hi:[1,0]
	v_pk_mul_f32 v[38:39], v[38:39], v[132:133] op_sel_hi:[1,0]
	v_pk_mul_f32 v[40:41], v[40:41], v[132:133] op_sel:[0,1]
	v_pk_mul_f32 v[42:43], v[42:43], v[132:133] op_sel:[0,1]
	v_pk_mul_f32 v[44:45], v[44:45], v[132:133] op_sel:[0,1]
	v_pk_mul_f32 v[46:47], v[46:47], v[132:133] op_sel:[0,1]
	v_pk_mul_f32 v[48:49], v[48:49], v[134:135] op_sel_hi:[1,0]
	v_pk_mul_f32 v[50:51], v[50:51], v[134:135] op_sel_hi:[1,0]
	v_pk_mul_f32 v[52:53], v[52:53], v[134:135] op_sel_hi:[1,0]
	v_pk_mul_f32 v[54:55], v[54:55], v[134:135] op_sel_hi:[1,0]
	v_pk_mul_f32 v[56:57], v[56:57], v[134:135] op_sel:[0,1]
	v_pk_mul_f32 v[58:59], v[58:59], v[134:135] op_sel:[0,1]
	v_pk_mul_f32 v[60:61], v[60:61], v[134:135] op_sel:[0,1]
	v_pk_mul_f32 v[62:63], v[62:63], v[134:135] op_sel:[0,1]
	v_cvt_pk_bf16_f32 v144, v0, v8
	v_cvt_pk_bf16_f32 v145, v16, v24
	v_cvt_pk_bf16_f32 v146, v32, v40
	v_cvt_pk_bf16_f32 v147, v48, v56
	global_store_dwordx4 v179, v[144:147], s[16:17]
	v_cvt_pk_bf16_f32 v148, v1, v9
	v_cvt_pk_bf16_f32 v149, v17, v25
	v_cvt_pk_bf16_f32 v150, v33, v41
	v_cvt_pk_bf16_f32 v151, v49, v57
	s_add_u32 s16, s16, s20
	s_addc_u32 s17, s17, 0
	global_store_dwordx4 v179, v[148:151], s[16:17]
	v_cvt_pk_bf16_f32 v152, v2, v10
	v_cvt_pk_bf16_f32 v153, v18, v26
	v_cvt_pk_bf16_f32 v154, v34, v42
	v_cvt_pk_bf16_f32 v155, v50, v58
	s_add_u32 s16, s16, s20
	s_addc_u32 s17, s17, 0
	global_store_dwordx4 v179, v[152:155], s[16:17]
	v_cvt_pk_bf16_f32 v156, v3, v11
	v_cvt_pk_bf16_f32 v157, v19, v27
	v_cvt_pk_bf16_f32 v158, v35, v43
	v_cvt_pk_bf16_f32 v159, v51, v59
	s_add_u32 s16, s16, s20
	s_addc_u32 s17, s17, 0
	global_store_dwordx4 v179, v[156:159], s[16:17]
	v_cvt_pk_bf16_f32 v160, v4, v12
	v_cvt_pk_bf16_f32 v161, v20, v28
	v_cvt_pk_bf16_f32 v162, v36, v44
	v_cvt_pk_bf16_f32 v163, v52, v60
	s_mul_i32 s2, s20, 29
	s_add_u32 s16, s16, s2
	s_addc_u32 s17, s17, 0
	global_store_dwordx4 v179, v[160:163], s[16:17]
	v_cvt_pk_bf16_f32 v164, v5, v13
	v_cvt_pk_bf16_f32 v165, v21, v29
	v_cvt_pk_bf16_f32 v166, v37, v45
	v_cvt_pk_bf16_f32 v167, v53, v61
	s_add_u32 s16, s16, s20
	s_addc_u32 s17, s17, 0
	global_store_dwordx4 v179, v[164:167], s[16:17]
	v_cvt_pk_bf16_f32 v168, v6, v14
	v_cvt_pk_bf16_f32 v169, v22, v30
	v_cvt_pk_bf16_f32 v170, v38, v46
	v_cvt_pk_bf16_f32 v171, v54, v62
	s_add_u32 s16, s16, s20
	s_addc_u32 s17, s17, 0
	global_store_dwordx4 v179, v[168:171], s[16:17]
	v_cvt_pk_bf16_f32 v172, v7, v15
	v_cvt_pk_bf16_f32 v173, v23, v31
	v_cvt_pk_bf16_f32 v174, v39, v47
	v_cvt_pk_bf16_f32 v175, v55, v63
	s_add_u32 s16, s16, s20
	s_addc_u32 s17, s17, 0
	global_store_dwordx4 v179, v[172:175], s[16:17]
	s_cmp_lt_u32 s4, 0x1424
	s_cbranch_scc1 .Lcv2_la_go
	s_mov_b32 s22, 0
	s_branch .Lcv2_la_end

.Lcv2_wb_wd:
	v_mad_u32_u24 v179, v185, s27, v186
	v_pk_mul_f32 v[64:65], v[64:65], v[136:137] op_sel_hi:[1,0]
	v_pk_mul_f32 v[66:67], v[66:67], v[136:137] op_sel_hi:[1,0]
	v_pk_mul_f32 v[68:69], v[68:69], v[136:137] op_sel_hi:[1,0]
	v_pk_mul_f32 v[70:71], v[70:71], v[136:137] op_sel_hi:[1,0]
	v_pk_mul_f32 v[72:73], v[72:73], v[136:137] op_sel:[0,1]
	v_pk_mul_f32 v[74:75], v[74:75], v[136:137] op_sel:[0,1]
	v_pk_mul_f32 v[76:77], v[76:77], v[136:137] op_sel:[0,1]
	v_pk_mul_f32 v[78:79], v[78:79], v[136:137] op_sel:[0,1]
	v_pk_mul_f32 v[80:81], v[80:81], v[138:139] op_sel_hi:[1,0]
	v_pk_mul_f32 v[82:83], v[82:83], v[138:139] op_sel_hi:[1,0]
	v_pk_mul_f32 v[84:85], v[84:85], v[138:139] op_sel_hi:[1,0]
	v_pk_mul_f32 v[86:87], v[86:87], v[138:139] op_sel_hi:[1,0]
	v_pk_mul_f32 v[88:89], v[88:89], v[138:139] op_sel:[0,1]
	v_pk_mul_f32 v[90:91], v[90:91], v[138:139] op_sel:[0,1]
	v_pk_mul_f32 v[92:93], v[92:93], v[138:139] op_sel:[0,1]
	v_pk_mul_f32 v[94:95], v[94:95], v[138:139] op_sel:[0,1]
	v_pk_mul_f32 v[96:97], v[96:97], v[140:141] op_sel_hi:[1,0]
	v_pk_mul_f32 v[98:99], v[98:99], v[140:141] op_sel_hi:[1,0]
	v_pk_mul_f32 v[100:101], v[100:101], v[140:141] op_sel_hi:[1,0]
	v_pk_mul_f32 v[102:103], v[102:103], v[140:141] op_sel_hi:[1,0]
	v_pk_mul_f32 v[104:105], v[104:105], v[140:141] op_sel:[0,1]
	v_pk_mul_f32 v[106:107], v[106:107], v[140:141] op_sel:[0,1]
	v_pk_mul_f32 v[108:109], v[108:109], v[140:141] op_sel:[0,1]
	v_pk_mul_f32 v[110:111], v[110:111], v[140:141] op_sel:[0,1]
	v_pk_mul_f32 v[112:113], v[112:113], v[142:143] op_sel_hi:[1,0]
	v_pk_mul_f32 v[114:115], v[114:115], v[142:143] op_sel_hi:[1,0]
	v_pk_mul_f32 v[116:117], v[116:117], v[142:143] op_sel_hi:[1,0]
	v_pk_mul_f32 v[118:119], v[118:119], v[142:143] op_sel_hi:[1,0]
	v_pk_mul_f32 v[120:121], v[120:121], v[142:143] op_sel:[0,1]
	v_pk_mul_f32 v[122:123], v[122:123], v[142:143] op_sel:[0,1]
	v_pk_mul_f32 v[124:125], v[124:125], v[142:143] op_sel:[0,1]
	v_pk_mul_f32 v[126:127], v[126:127], v[142:143] op_sel:[0,1]
	v_cvt_pk_bf16_f32 v144, v64, v72
	v_cvt_pk_bf16_f32 v145, v80, v88
	v_cvt_pk_bf16_f32 v146, v96, v104
	v_cvt_pk_bf16_f32 v147, v112, v120
	global_store_dwordx4 v179, v[144:147], s[24:25]
	v_cvt_pk_bf16_f32 v148, v65, v73
	v_cvt_pk_bf16_f32 v149, v81, v89
	v_cvt_pk_bf16_f32 v150, v97, v105
	v_cvt_pk_bf16_f32 v151, v113, v121
	s_add_u32 s24, s24, s26
	s_addc_u32 s25, s25, 0
	global_store_dwordx4 v179, v[148:151], s[24:25]
	v_cvt_pk_bf16_f32 v152, v66, v74
	v_cvt_pk_bf16_f32 v153, v82, v90
	v_cvt_pk_bf16_f32 v154, v98, v106
	v_cvt_pk_bf16_f32 v155, v114, v122
	s_add_u32 s24, s24, s26
	s_addc_u32 s25, s25, 0
	global_store_dwordx4 v179, v[152:155], s[24:25]
	v_cvt_pk_bf16_f32 v156, v67, v75
	v_cvt_pk_bf16_f32 v157, v83, v91
	v_cvt_pk_bf16_f32 v158, v99, v107
	v_cvt_pk_bf16_f32 v159, v115, v123
	s_add_u32 s24, s24, s26
	s_addc_u32 s25, s25, 0
	global_store_dwordx4 v179, v[156:159], s[24:25]
	v_cvt_pk_bf16_f32 v160, v68, v76
	v_cvt_pk_bf16_f32 v161, v84, v92
	v_cvt_pk_bf16_f32 v162, v100, v108
	v_cvt_pk_bf16_f32 v163, v116, v124
	s_mul_i32 s2, s26, 29
	s_add_u32 s24, s24, s2
	s_addc_u32 s25, s25, 0
	global_store_dwordx4 v179, v[160:163], s[24:25]
	v_cvt_pk_bf16_f32 v164, v69, v77
	v_cvt_pk_bf16_f32 v165, v85, v93
	v_cvt_pk_bf16_f32 v166, v101, v109
	v_cvt_pk_bf16_f32 v167, v117, v125
	s_add_u32 s24, s24, s26
	s_addc_u32 s25, s25, 0
	global_store_dwordx4 v179, v[164:167], s[24:25]
	v_cvt_pk_bf16_f32 v168, v70, v78
	v_cvt_pk_bf16_f32 v169, v86, v94
	v_cvt_pk_bf16_f32 v170, v102, v110
	v_cvt_pk_bf16_f32 v171, v118, v126
	s_add_u32 s24, s24, s26
	s_addc_u32 s25, s25, 0
	global_store_dwordx4 v179, v[168:171], s[24:25]
	v_cvt_pk_bf16_f32 v172, v71, v79
	v_cvt_pk_bf16_f32 v173, v87, v95
	v_cvt_pk_bf16_f32 v174, v103, v111
	v_cvt_pk_bf16_f32 v175, v119, v127
	s_add_u32 s24, s24, s26
	s_addc_u32 s25, s25, 0
	global_store_dwordx4 v179, v[172:175], s[24:25]
	s_cmp_lt_u32 s4, 0x1424
	s_cbranch_scc1 .Lcv2_lb_go
	s_mov_b32 s28, 0
	s_branch .Lcv2_lb_end
